# v34: v33 + non-temporal hint on final-norm row loads and OUT-GEMM residual (x) loads
# speedup vs baseline: 1.0144x; 1.0002x over previous
.LBB0_1425:
	v_mov_b32_e32 v64, v166
	s_waitcnt lgkmcnt(0)
	s_barrier
	v_add_u32_e32 v65, s5, v138
	v_and_b32_e32 v66, 31, v64
	v_lshrrev_b32_e32 v64, 3, v64
	v_and_or_b32 v86, v64, 4, v65
	s_lshl_b32 s26, s3, 2
	v_lshl_add_u64 v[64:65], v[130:131], 0, s[26:27]
	v_lshlrev_b32_e32 v128, 2, v66
	v_ashrrev_i32_e32 v87, 31, v86
	v_or_b32_e32 v66, 1, v86
	v_or_b32_e32 v68, 2, v86
	v_or_b32_e32 v70, 3, v86
	v_or_b32_e32 v72, 8, v86
	v_or_b32_e32 v74, 9, v86
	v_or_b32_e32 v76, 10, v86
	v_or_b32_e32 v78, 11, v86
	v_or_b32_e32 v80, 16, v86
	v_or_b32_e32 v82, 17, v86
	v_or_b32_e32 v84, 18, v86
	v_or_b32_e32 v88, 19, v86
	v_or_b32_e32 v92, 24, v86
	v_or_b32_e32 v94, 25, v86
	v_or_b32_e32 v96, 26, v86
	v_or_b32_e32 v134, 27, v86
	v_lshl_add_u64 v[90:91], v[64:65], 0, v[128:129]
	v_lshlrev_b64 v[64:65], 12, v[86:87]
	v_ashrrev_i32_e32 v67, 31, v66
	v_ashrrev_i32_e32 v69, 31, v68
	v_ashrrev_i32_e32 v71, 31, v70
	v_ashrrev_i32_e32 v73, 31, v72
	v_ashrrev_i32_e32 v75, 31, v74
	v_ashrrev_i32_e32 v77, 31, v76
	v_ashrrev_i32_e32 v79, 31, v78
	v_ashrrev_i32_e32 v81, 31, v80
	v_ashrrev_i32_e32 v83, 31, v82
	v_ashrrev_i32_e32 v85, 31, v84
	v_ashrrev_i32_e32 v89, 31, v88
	v_ashrrev_i32_e32 v93, 31, v92
	v_ashrrev_i32_e32 v95, 31, v94
	v_ashrrev_i32_e32 v97, 31, v96
	v_ashrrev_i32_e32 v135, 31, v134
	v_lshl_add_u64 v[98:99], v[90:91], 0, v[64:65]
	v_lshlrev_b64 v[66:67], 12, v[66:67]
	v_lshlrev_b64 v[68:69], 12, v[68:69]
	v_lshlrev_b64 v[70:71], 12, v[70:71]
	v_lshlrev_b64 v[72:73], 12, v[72:73]
	v_lshlrev_b64 v[74:75], 12, v[74:75]
	v_lshlrev_b64 v[76:77], 12, v[76:77]
	v_lshlrev_b64 v[78:79], 12, v[78:79]
	v_lshlrev_b64 v[80:81], 12, v[80:81]
	v_lshlrev_b64 v[82:83], 12, v[82:83]
	v_lshlrev_b64 v[84:85], 12, v[84:85]
	v_lshlrev_b64 v[88:89], 12, v[88:89]
	v_lshlrev_b64 v[92:93], 12, v[92:93]
	v_lshlrev_b64 v[94:95], 12, v[94:95]
	v_lshlrev_b64 v[96:97], 12, v[96:97]
	v_lshlrev_b64 v[134:135], 12, v[134:135]
	v_lshl_add_u64 v[100:101], v[90:91], 0, v[66:67]
	v_lshl_add_u64 v[102:103], v[90:91], 0, v[68:69]
	v_lshl_add_u64 v[104:105], v[90:91], 0, v[70:71]
	v_lshl_add_u64 v[106:107], v[90:91], 0, v[72:73]
	v_lshl_add_u64 v[108:109], v[90:91], 0, v[74:75]
	v_lshl_add_u64 v[110:111], v[90:91], 0, v[76:77]
	v_lshl_add_u64 v[112:113], v[90:91], 0, v[78:79]
	v_lshl_add_u64 v[114:115], v[90:91], 0, v[80:81]
	v_lshl_add_u64 v[116:117], v[90:91], 0, v[82:83]
	v_lshl_add_u64 v[118:119], v[90:91], 0, v[84:85]
	v_lshl_add_u64 v[120:121], v[90:91], 0, v[88:89]
	v_lshl_add_u64 v[122:123], v[90:91], 0, v[92:93]
	v_lshl_add_u64 v[124:125], v[90:91], 0, v[94:95]
	v_lshl_add_u64 v[126:127], v[90:91], 0, v[96:97]
	v_lshl_add_u64 v[162:163], v[90:91], 0, v[134:135]
	global_load_dword v161, v[98:99], off nt
	global_load_dword v167, v[100:101], off nt
	global_load_dword v194, v[102:103], off nt
	global_load_dword v195, v[104:105], off nt
	global_load_dword v196, v[104:105], off offset:128 nt
	global_load_dword v197, v[102:103], off offset:128 nt
	global_load_dword v198, v[100:101], off offset:128 nt
	global_load_dword v199, v[98:99], off offset:128 nt
	global_load_dword v200, v[106:107], off nt
	global_load_dword v201, v[108:109], off nt
	global_load_dword v202, v[110:111], off nt
	global_load_dword v203, v[112:113], off nt
	global_load_dword v204, v[112:113], off offset:128 nt
	global_load_dword v205, v[110:111], off offset:128 nt
	global_load_dword v206, v[108:109], off offset:128 nt
	global_load_dword v207, v[106:107], off offset:128 nt
	global_load_dword v208, v[114:115], off nt
	global_load_dword v209, v[116:117], off nt
	global_load_dword v210, v[118:119], off nt
	global_load_dword v211, v[120:121], off nt
	global_load_dword v212, v[120:121], off offset:128 nt
	global_load_dword v213, v[118:119], off offset:128 nt
	global_load_dword v214, v[116:117], off offset:128 nt
	global_load_dword v215, v[114:115], off offset:128 nt
	global_load_dword v216, v[122:123], off nt
	global_load_dword v217, v[124:125], off nt
	global_load_dword v218, v[126:127], off nt
	global_load_dword v219, v[162:163], off nt
	global_load_dword v220, v[162:163], off offset:128 nt
	global_load_dword v221, v[126:127], off offset:128 nt
	global_load_dword v222, v[124:125], off offset:128 nt
	global_load_dword v223, v[122:123], off offset:128 nt
	v_or_b32_e32 v98, 32, v86
	v_or_b32_e32 v102, 33, v86
	v_or_b32_e32 v106, 34, v86
	v_or_b32_e32 v110, 35, v86
	v_or_b32_e32 v114, 40, v86
	v_or_b32_e32 v118, 41, v86
	v_or_b32_e32 v122, 42, v86
	v_or_b32_e32 v126, 43, v86
	v_or_b32_e32 v164, 48, v86
	v_or_b32_e32 v170, 49, v86
	v_or_b32_e32 v174, 50, v86
	v_or_b32_e32 v178, 51, v86
	v_or_b32_e32 v182, 56, v86
	v_or_b32_e32 v186, 57, v86
	v_or_b32_e32 v190, 58, v86
	v_ashrrev_i32_e32 v99, 31, v98
	v_ashrrev_i32_e32 v103, 31, v102
	v_ashrrev_i32_e32 v107, 31, v106
	v_ashrrev_i32_e32 v111, 31, v110
	v_ashrrev_i32_e32 v115, 31, v114
	v_ashrrev_i32_e32 v119, 31, v118
	v_ashrrev_i32_e32 v123, 31, v122
	v_ashrrev_i32_e32 v127, 31, v126
	v_ashrrev_i32_e32 v165, 31, v164
	v_ashrrev_i32_e32 v171, 31, v170
	v_ashrrev_i32_e32 v175, 31, v174
	v_ashrrev_i32_e32 v179, 31, v178
	v_ashrrev_i32_e32 v183, 31, v182
	v_ashrrev_i32_e32 v187, 31, v186
	v_ashrrev_i32_e32 v191, 31, v190
	v_or_b32_e32 v86, 59, v86
	v_lshlrev_b64 v[98:99], 12, v[98:99]
	v_lshlrev_b64 v[102:103], 12, v[102:103]
	v_lshlrev_b64 v[106:107], 12, v[106:107]
	v_lshlrev_b64 v[110:111], 12, v[110:111]
	v_lshlrev_b64 v[114:115], 12, v[114:115]
	v_lshlrev_b64 v[118:119], 12, v[118:119]
	v_lshlrev_b64 v[122:123], 12, v[122:123]
	v_lshlrev_b64 v[126:127], 12, v[126:127]
	v_lshlrev_b64 v[164:165], 12, v[164:165]
	v_lshlrev_b64 v[170:171], 12, v[170:171]
	v_lshlrev_b64 v[174:175], 12, v[174:175]
	v_lshlrev_b64 v[178:179], 12, v[178:179]
	v_lshlrev_b64 v[182:183], 12, v[182:183]
	v_lshlrev_b64 v[186:187], 12, v[186:187]
	v_lshlrev_b64 v[190:191], 12, v[190:191]
	v_ashrrev_i32_e32 v87, 31, v86
	v_lshl_add_u64 v[100:101], v[90:91], 0, v[98:99]
	v_lshl_add_u64 v[104:105], v[90:91], 0, v[102:103]
	v_lshl_add_u64 v[108:109], v[90:91], 0, v[106:107]
	v_lshl_add_u64 v[112:113], v[90:91], 0, v[110:111]
	v_lshl_add_u64 v[116:117], v[90:91], 0, v[114:115]
	v_lshl_add_u64 v[120:121], v[90:91], 0, v[118:119]
	v_lshl_add_u64 v[124:125], v[90:91], 0, v[122:123]
	v_lshl_add_u64 v[162:163], v[90:91], 0, v[126:127]
	v_lshl_add_u64 v[168:169], v[90:91], 0, v[164:165]
	v_lshl_add_u64 v[172:173], v[90:91], 0, v[170:171]
	v_lshl_add_u64 v[176:177], v[90:91], 0, v[174:175]
	v_lshl_add_u64 v[180:181], v[90:91], 0, v[178:179]
	v_lshl_add_u64 v[184:185], v[90:91], 0, v[182:183]
	v_lshl_add_u64 v[188:189], v[90:91], 0, v[186:187]
	v_lshl_add_u64 v[192:193], v[90:91], 0, v[190:191]
	v_lshlrev_b64 v[86:87], 12, v[86:87]
	v_lshl_add_u64 v[90:91], v[90:91], 0, v[86:87]
	global_load_dword v224, v[100:101], off nt
	global_load_dword v225, v[104:105], off nt
	global_load_dword v226, v[108:109], off nt
	global_load_dword v227, v[112:113], off nt
	s_nop 0
	global_load_dword v112, v[112:113], off offset:128 nt
	s_nop 0
	global_load_dword v108, v[108:109], off offset:128 nt
	s_nop 0
	global_load_dword v104, v[104:105], off offset:128 nt
	s_nop 0
	global_load_dword v100, v[100:101], off offset:128 nt
	s_nop 0
	global_load_dword v101, v[116:117], off nt
	global_load_dword v105, v[120:121], off nt
	global_load_dword v109, v[124:125], off nt
	global_load_dword v113, v[162:163], off nt
	s_nop 0
	global_load_dword v162, v[162:163], off offset:128 nt
	s_nop 0
	global_load_dword v124, v[124:125], off offset:128 nt
	s_nop 0
	global_load_dword v120, v[120:121], off offset:128 nt
	s_nop 0
	global_load_dword v116, v[116:117], off offset:128 nt
	s_nop 0
	global_load_dword v117, v[168:169], off nt
	global_load_dword v121, v[172:173], off nt
	global_load_dword v125, v[176:177], off nt
	global_load_dword v163, v[180:181], off nt
	s_nop 0
	global_load_dword v180, v[180:181], off offset:128 nt
	s_nop 0
	global_load_dword v176, v[176:177], off offset:128 nt
	s_nop 0
	global_load_dword v172, v[172:173], off offset:128 nt
	s_nop 0
	global_load_dword v168, v[168:169], off offset:128 nt
	s_nop 0
	global_load_dword v169, v[184:185], off nt
	global_load_dword v173, v[188:189], off nt
	global_load_dword v177, v[192:193], off nt
	global_load_dword v181, v[90:91], off nt
	global_load_dword v228, v[90:91], off offset:128 nt
	s_nop 0
	global_load_dword v192, v[192:193], off offset:128 nt
	s_nop 0
	global_load_dword v188, v[188:189], off offset:128 nt
	s_nop 0
	global_load_dword v184, v[184:185], off offset:128 nt
	v_lshl_add_u64 v[90:91], v[132:133], 0, s[26:27]
	v_lshl_add_u64 v[90:91], v[90:91], 0, v[128:129]
	s_waitcnt vmcnt(0)
	v_add_f32_e32 v48, v48, v161
	v_lshl_add_u64 v[64:65], v[90:91], 0, v[64:65]
	v_add_f32_e32 v32, v32, v199
	global_store_dword v[64:65], v48, off sc0 sc1
	v_add_f32_e32 v128, v49, v167
	v_lshl_add_u64 v[48:49], v[90:91], 0, v[66:67]
	global_store_dword v[64:65], v32, off offset:128 sc0 sc1
	v_add_f32_e32 v32, v33, v198
	v_add_f32_e32 v50, v50, v194
	v_lshl_add_u64 v[66:67], v[90:91], 0, v[68:69]
	global_store_dword v[48:49], v32, off offset:128 sc0 sc1
	v_add_f32_e32 v32, v34, v197
	global_store_dword v[66:67], v50, off sc0 sc1
	v_add_f32_e32 v68, v51, v195
	v_lshl_add_u64 v[50:51], v[90:91], 0, v[70:71]
	global_store_dword v[66:67], v32, off offset:128 sc0 sc1
	v_add_f32_e32 v32, v35, v196
	global_store_dword v[50:51], v68, off sc0 sc1
	v_add_f32_e32 v52, v52, v200
	v_lshl_add_u64 v[68:69], v[90:91], 0, v[72:73]
	global_store_dword v[50:51], v32, off offset:128 sc0 sc1
	v_add_f32_e32 v32, v36, v207
	global_store_dword v[68:69], v52, off sc0 sc1
	v_add_f32_e32 v70, v53, v201
	v_lshl_add_u64 v[52:53], v[90:91], 0, v[74:75]
	global_store_dword v[68:69], v32, off offset:128 sc0 sc1
	v_add_f32_e32 v32, v37, v206
	global_store_dword v[52:53], v70, off sc0 sc1
	v_add_f32_e32 v54, v54, v202
	v_lshl_add_u64 v[70:71], v[90:91], 0, v[76:77]
	global_store_dword v[52:53], v32, off offset:128 sc0 sc1
	v_add_f32_e32 v32, v38, v205
	global_store_dword v[70:71], v54, off sc0 sc1
	v_add_f32_e32 v72, v55, v203
	v_lshl_add_u64 v[54:55], v[90:91], 0, v[78:79]
	global_store_dword v[70:71], v32, off offset:128 sc0 sc1
	v_add_f32_e32 v32, v39, v204
	global_store_dword v[54:55], v72, off sc0 sc1
	v_add_f32_e32 v56, v56, v208
	v_lshl_add_u64 v[72:73], v[90:91], 0, v[80:81]
	global_store_dword v[54:55], v32, off offset:128 sc0 sc1
	v_add_f32_e32 v32, v40, v215
	global_store_dword v[72:73], v56, off sc0 sc1
	v_add_f32_e32 v74, v57, v209
	v_lshl_add_u64 v[56:57], v[90:91], 0, v[82:83]
	global_store_dword v[72:73], v32, off offset:128 sc0 sc1
	v_add_f32_e32 v32, v41, v214
	global_store_dword v[56:57], v74, off sc0 sc1
	v_add_f32_e32 v58, v58, v210
	v_lshl_add_u64 v[74:75], v[90:91], 0, v[84:85]
	global_store_dword v[56:57], v32, off offset:128 sc0 sc1
	v_add_f32_e32 v32, v42, v213
	global_store_dword v[74:75], v58, off sc0 sc1
	v_add_f32_e32 v76, v59, v211
	v_lshl_add_u64 v[58:59], v[90:91], 0, v[88:89]
	global_store_dword v[74:75], v32, off offset:128 sc0 sc1
	v_add_f32_e32 v32, v43, v212
	global_store_dword v[58:59], v76, off sc0 sc1
	v_add_f32_e32 v60, v60, v216
	v_lshl_add_u64 v[76:77], v[90:91], 0, v[92:93]
	global_store_dword v[58:59], v32, off offset:128 sc0 sc1
	v_add_f32_e32 v32, v44, v223
	global_store_dword v[76:77], v60, off sc0 sc1
	v_add_f32_e32 v78, v61, v217
	v_lshl_add_u64 v[60:61], v[90:91], 0, v[94:95]
	global_store_dword v[76:77], v32, off offset:128 sc0 sc1
	v_add_f32_e32 v32, v45, v222
	global_store_dword v[60:61], v78, off sc0 sc1
	v_add_f32_e32 v62, v62, v218
	v_lshl_add_u64 v[78:79], v[90:91], 0, v[96:97]
	global_store_dword v[60:61], v32, off offset:128 sc0 sc1
	v_add_f32_e32 v32, v46, v221
	global_store_dword v[78:79], v62, off sc0 sc1
	v_add_f32_e32 v80, v63, v219
	v_lshl_add_u64 v[62:63], v[90:91], 0, v[134:135]
	global_store_dword v[78:79], v32, off offset:128 sc0 sc1
	v_add_f32_e32 v32, v47, v220
	global_store_dword v[62:63], v32, off offset:128 sc0 sc1
	v_add_f32_e32 v16, v16, v224
	v_lshl_add_u64 v[32:33], v[90:91], 0, v[98:99]
	v_add_f32_e32 v0, v0, v100
	global_store_dword v[32:33], v16, off sc0 sc1
	v_add_f32_e32 v34, v17, v225
	v_lshl_add_u64 v[16:17], v[90:91], 0, v[102:103]
	global_store_dword v[32:33], v0, off offset:128 sc0 sc1
	v_add_f32_e32 v0, v1, v104
	global_store_dword v[16:17], v34, off sc0 sc1
	v_add_f32_e32 v18, v18, v226
	v_lshl_add_u64 v[34:35], v[90:91], 0, v[106:107]
	global_store_dword v[16:17], v0, off offset:128 sc0 sc1
	v_add_f32_e32 v0, v2, v108
	global_store_dword v[34:35], v18, off sc0 sc1
	v_add_f32_e32 v36, v19, v227
	v_lshl_add_u64 v[18:19], v[90:91], 0, v[110:111]
	global_store_dword v[34:35], v0, off offset:128 sc0 sc1
	v_add_f32_e32 v0, v3, v112
	global_store_dword v[18:19], v36, off sc0 sc1
	v_add_f32_e32 v20, v20, v101
	v_lshl_add_u64 v[36:37], v[90:91], 0, v[114:115]
	global_store_dword v[18:19], v0, off offset:128 sc0 sc1
	v_add_f32_e32 v0, v4, v116
	global_store_dword v[36:37], v20, off sc0 sc1
	v_add_f32_e32 v38, v21, v105
	v_lshl_add_u64 v[20:21], v[90:91], 0, v[118:119]
	global_store_dword v[36:37], v0, off offset:128 sc0 sc1
	v_add_f32_e32 v0, v5, v120
	global_store_dword v[20:21], v38, off sc0 sc1
	v_add_f32_e32 v22, v22, v109
	v_lshl_add_u64 v[38:39], v[90:91], 0, v[122:123]
	global_store_dword v[20:21], v0, off offset:128 sc0 sc1
	v_add_f32_e32 v0, v6, v124
	global_store_dword v[38:39], v22, off sc0 sc1
	v_add_f32_e32 v40, v23, v113
	v_lshl_add_u64 v[22:23], v[90:91], 0, v[126:127]
	global_store_dword v[38:39], v0, off offset:128 sc0 sc1
	v_add_f32_e32 v0, v7, v162
	global_store_dword v[22:23], v40, off sc0 sc1
	v_add_f32_e32 v24, v24, v117
	v_lshl_add_u64 v[40:41], v[90:91], 0, v[164:165]
	global_store_dword v[22:23], v0, off offset:128 sc0 sc1
	v_add_f32_e32 v0, v8, v168
	global_store_dword v[40:41], v24, off sc0 sc1
	v_add_f32_e32 v42, v25, v121
	v_lshl_add_u64 v[24:25], v[90:91], 0, v[170:171]
	global_store_dword v[40:41], v0, off offset:128 sc0 sc1
	v_add_f32_e32 v0, v9, v172
	global_store_dword v[24:25], v42, off sc0 sc1
	v_add_f32_e32 v26, v26, v125
	v_lshl_add_u64 v[42:43], v[90:91], 0, v[174:175]
	global_store_dword v[24:25], v0, off offset:128 sc0 sc1
	v_add_f32_e32 v0, v10, v176
	global_store_dword v[42:43], v26, off sc0 sc1
	v_add_f32_e32 v44, v27, v163
	v_lshl_add_u64 v[26:27], v[90:91], 0, v[178:179]
	global_store_dword v[42:43], v0, off offset:128 sc0 sc1
	v_add_f32_e32 v0, v11, v180
	global_store_dword v[26:27], v44, off sc0 sc1
	v_add_f32_e32 v28, v28, v169
	v_lshl_add_u64 v[44:45], v[90:91], 0, v[182:183]
	global_store_dword v[26:27], v0, off offset:128 sc0 sc1
	v_add_f32_e32 v0, v12, v184
	global_store_dword v[44:45], v28, off sc0 sc1
	v_add_f32_e32 v46, v29, v173
	v_lshl_add_u64 v[28:29], v[90:91], 0, v[186:187]
	global_store_dword v[44:45], v0, off offset:128 sc0 sc1
	v_add_f32_e32 v0, v13, v188
	global_store_dword v[28:29], v46, off sc0 sc1
	v_add_f32_e32 v30, v30, v177
	v_lshl_add_u64 v[46:47], v[90:91], 0, v[190:191]
	global_store_dword v[28:29], v0, off offset:128 sc0 sc1
	v_add_f32_e32 v0, v14, v192
	s_add_i32 s38, s38, s37
	s_add_i32 s0, s0, s1
	global_store_dword v[48:49], v128, off sc0 sc1
	global_store_dword v[46:47], v30, off sc0 sc1
	v_add_f32_e32 v48, v31, v181
	v_lshl_add_u64 v[30:31], v[90:91], 0, v[86:87]
	global_store_dword v[46:47], v0, off offset:128 sc0 sc1
	v_add_f32_e32 v0, v15, v228
	s_cmpk_lt_i32 s38, 0x400
	global_store_dword v[62:63], v80, off sc0 sc1
	global_store_dword v[30:31], v48, off sc0 sc1
	global_store_dword v[30:31], v0, off offset:128 sc0 sc1
	s_waitcnt lgkmcnt(0)
	s_barrier
	s_cbranch_scc0 .LBB0_1456

.LBB0_1485:
	global_load_dwordx4 v[12:15], v[4:5], off nt
	global_load_dwordx4 v[16:19], v[4:5], off offset:1024 nt
	global_load_dwordx4 v[20:23], v[4:5], off offset:2048 nt
	global_load_dwordx4 v[24:27], v[4:5], off offset:3072 nt
	global_load_dwordx4 v[28:31], v[2:3], off
	v_add_u32_e32 v0, s4, v0
	s_waitcnt vmcnt(4)
	v_mov_b32_e32 v34, v13
	s_waitcnt vmcnt(3)
	v_mov_b32_e32 v35, v17
	v_mov_b32_e32 v32, v12
	v_mov_b32_e32 v33, v16
	s_waitcnt vmcnt(2)
	v_mov_b32_e32 v42, v21
	s_waitcnt vmcnt(1)
	v_mov_b32_e32 v43, v25
	v_pk_mul_f32 v[34:35], v[34:35], v[34:35]
	v_mov_b32_e32 v36, v14
	v_mov_b32_e32 v37, v18
	v_mov_b32_e32 v40, v20
	v_mov_b32_e32 v41, v24
	v_pk_mul_f32 v[42:43], v[42:43], v[42:43]
	v_pk_fma_f32 v[32:33], v[32:33], v[32:33], v[34:35]
	v_mov_b32_e32 v38, v15
	v_mov_b32_e32 v39, v19
	v_mov_b32_e32 v44, v22
	v_mov_b32_e32 v45, v26
	v_pk_fma_f32 v[34:35], v[40:41], v[40:41], v[42:43]
	v_pk_fma_f32 v[32:33], v[36:37], v[36:37], v[32:33]
	v_mov_b32_e32 v46, v23
	v_mov_b32_e32 v47, v27
	v_pk_fma_f32 v[34:35], v[44:45], v[44:45], v[34:35]
	v_pk_fma_f32 v[32:33], v[38:39], v[38:39], v[32:33]
	v_pk_fma_f32 v[34:35], v[46:47], v[46:47], v[34:35]
	v_add_f32_e32 v32, v32, v33
	v_add_f32_e32 v32, v32, v34
	v_add_f32_e32 v32, v32, v35
	ds_bpermute_b32 v33, v6, v32
	s_waitcnt lgkmcnt(0)
	v_add_f32_e32 v32, v32, v33
	ds_bpermute_b32 v33, v7, v32
	s_waitcnt lgkmcnt(0)
	v_add_f32_e32 v32, v32, v33
	ds_bpermute_b32 v33, v8, v32
	s_waitcnt lgkmcnt(0)
	v_add_f32_e32 v32, v32, v33
	ds_bpermute_b32 v33, v9, v32
	s_waitcnt lgkmcnt(0)
	v_add_f32_e32 v32, v32, v33
	ds_bpermute_b32 v33, v10, v32
	s_waitcnt lgkmcnt(0)
	v_add_f32_e32 v32, v32, v33
	ds_bpermute_b32 v33, v11, v32
	s_waitcnt lgkmcnt(0)
	v_add_f32_e32 v32, v32, v33
	v_fmamk_f32 v32, v32, 0x3a800000, v1
	v_mul_f32_e32 v33, 0x4b800000, v32
	v_cmp_gt_f32_e32 vcc, s5, v32
	s_nop 1
	v_cndmask_b32_e32 v32, v32, v33, vcc
	v_rsq_f32_e32 v32, v32
	s_nop 0
	v_mul_f32_e32 v33, 0x45800000, v32
	v_cndmask_b32_e32 v32, v32, v33, vcc
	s_waitcnt vmcnt(0)
	v_pk_mul_f32 v[28:29], v[28:29], v[32:33] op_sel_hi:[1,0]
	v_pk_mul_f32 v[30:31], v[30:31], v[32:33] op_sel_hi:[1,0]
	v_pk_mul_f32 v[12:13], v[12:13], v[28:29]
	v_pk_mul_f32 v[14:15], v[14:15], v[30:31]
	global_store_dwordx4 v[4:5], v[12:15], off nt
	global_load_dwordx4 v[12:15], v[2:3], off offset:1024
	v_cmp_lt_i32_e32 vcc, s6, v0
	s_or_b64 s[2:3], vcc, s[2:3]
	s_waitcnt vmcnt(0)
	v_pk_mul_f32 v[14:15], v[14:15], v[32:33] op_sel_hi:[1,0]
	v_pk_mul_f32 v[12:13], v[12:13], v[32:33] op_sel_hi:[1,0]
	v_pk_mul_f32 v[14:15], v[18:19], v[14:15]
	v_pk_mul_f32 v[12:13], v[16:17], v[12:13]
	global_store_dwordx4 v[4:5], v[12:15], off offset:1024 nt
	global_load_dwordx4 v[12:15], v[2:3], off offset:2048
	s_waitcnt vmcnt(0)
	v_pk_mul_f32 v[14:15], v[32:33], v[14:15] op_sel_hi:[0,1]
	v_pk_mul_f32 v[12:13], v[32:33], v[12:13] op_sel_hi:[0,1]
	v_pk_mul_f32 v[12:13], v[20:21], v[12:13]
	v_pk_mul_f32 v[14:15], v[22:23], v[14:15]
	global_store_dwordx4 v[4:5], v[12:15], off offset:2048 nt
	global_load_dwordx4 v[12:15], v[2:3], off offset:3072
	s_waitcnt vmcnt(0)
	v_pk_mul_f32 v[14:15], v[32:33], v[14:15] op_sel_hi:[0,1]
	v_pk_mul_f32 v[12:13], v[32:33], v[12:13] op_sel_hi:[0,1]
	v_pk_mul_f32 v[12:13], v[24:25], v[12:13]
	v_pk_mul_f32 v[14:15], v[26:27], v[14:15]
	global_store_dwordx4 v[4:5], v[12:15], off offset:3072 nt
	v_lshl_add_u64 v[4:5], v[4:5], 0, s[0:1]
	s_andn2_b64 exec, exec, s[2:3]
	s_cbranch_execnz .LBB0_1485
